# plus: EpiF32 GEMM loop keeps 8 phases but issues first 4 MFMAs of each phase before the phase barrier
# speedup vs baseline: 1.0331x; 1.0021x over previous
; #define PG8_STAGE(bufoff, gbase, voff) do { _Pragma("unroll") for (int _i = 0; _i < 2; ++_i) \
;         __builtin_amdgcn_global_load_lds((const unsigned*)((const char*)(gbase) + (voff)[_i]), (LAS unsigned*)(lds + (bufoff) + ldsw + _i * 8192), 16, 0, 0); } while (0)
; #define PG8_LDA(dst, b, h) do { _Pragma("unroll") for (int m = 0; m < 4; ++m) _Pragma("unroll") for (int k = 0; k < 2; ++k) dst[m][k] = *(const LAS bf16x8*)(lds + PG8_SA(b, h) + aoff + m * 2048 + k * 1024); } while (0)
; #define PG8_LDB(dst, b, h) do { _Pragma("unroll") for (int n = 0; n < 2; ++n) _Pragma("unroll") for (int k = 0; k < 2; ++k) dst[n][k] = *(const LAS bf16x8*)(lds + PG8_SB(b, h) + boff + n * 2048 + k * 1024); } while (0)
; #define PG8_MMA(ai, bj, At, Bt) do { __builtin_amdgcn_s_setprio(1); _Pragma("unroll") for (int m = 0; m < 4; ++m) _Pragma("unroll") for (int n = 0; n < 2; ++n) _Pragma("unroll") for (int k = 0; k < 2; ++k) \
;         acc[ai][bj][m][n] = __builtin_amdgcn_mfma_f32_16x16x32_bf16(Bt[n][k], At[m][k], acc[ai][bj][m][n], 0, 0, 0); __builtin_amdgcn_s_setprio(0); } while (0)
; #define PG8_WAIT_L(n) asm volatile("s_waitcnt lgkmcnt(" #n ")" ::: "memory")
; #define PG8_BAR __builtin_amdgcn_s_barrier()
; #define PG8_SCHED __builtin_amdgcn_sched_barrier(0)
; template <class Epi>
; __device__ __forceinline__ void gemm_phase(LAS unsigned char* lds, const Gemm g, const Sched& S, const Epi& E) {
;     ...
;         for (int t = 0; t < nt; t += 2) {
;             const bool last = (t == nt - 2);
;             const char* a1 = cA + (size_t)(t + 1) * kstep;
;             const char* a2 = last ? nA : cA + (size_t)(t + 2) * kstep; const char* b2 = last ? nB : cB + (size_t)(t + 2) * kstep;
;             const char* a3 = a2 + kstep; const char* b3 = b2 + kstep;
;             PG8_LDB(B0, 0, 0); PG8_SCHED; PG8_LDA(At, 0, 0); PG8_STAGE(PG8_SA(1, 1), a1 + hstepA, voffA);
;             PG8_WAIT_L(8); PG8_BAR; PG8_WAIT_L(0); PG8_MMA(0, 0, At, B0); PG8_BAR; PG8_SCHED;
;             PG8_LDB(B1, 0, 1); PG8_STAGE(PG8_SB(0, 0), b2, voffB);
;             PG8_BAR; PG8_WAIT_L(0); PG8_MMA(0, 1, At, B1); PG8_BAR;
;             PG8_LDA(At, 0, 1); PG8_STAGE(PG8_SA(0, 0), a2, voffA);
;             PG8_BAR; PG8_WAIT_L(0); PG8_MMA(1, 0, At, B0); PG8_BAR; PG8_SCHED;
.LBB0_719:
	s_add_i32 s14, s4, 2
	s_add_u32 s15, s0, 0x80
	s_addc_u32 s5, s1, 0
	s_add_i32 s8, 0, 0x10000
	v_add_u32_e32 v118, s8, v217
	ds_read_b128 v[106:109], v118
	ds_read_b128 v[110:113], v118 offset:1024
	ds_read_b128 v[114:117], v118 offset:2048
	ds_read_b128 v[118:121], v118 offset:3072
	s_cmp_eq_u32 s48, s4
	s_cselect_b32 s4, s59, s15
	s_cselect_b32 s5, s57, s5
	s_cselect_b32 s95, vcc_lo, s35
	s_cselect_b32 s94, vcc_hi, s34
	v_lshl_add_u64 v[154:155], s[0:1], 0, v[202:203]
	s_add_i32 m0, s52, 0xc000
	ds_read_b128 v[122:125], v235
	ds_read_b128 v[126:129], v235 offset:1024
	ds_read_b128 v[130:133], v235 offset:2048
	ds_read_b128 v[134:137], v235 offset:3072
	ds_read_b128 v[138:141], v235 offset:4096
	ds_read_b128 v[142:145], v235 offset:5120
	ds_read_b128 v[146:149], v235 offset:6144
	ds_read_b128 v[150:153], v235 offset:7168
	global_load_lds_dwordx4 v[154:155], off
	v_lshl_add_u64 v[154:155], s[0:1], 0, v[204:205]
	s_add_i32 m0, s52, 0xe000
	s_nop 0
	global_load_lds_dwordx4 v[154:155], off
	s_waitcnt lgkmcnt(8)
	s_waitcnt lgkmcnt(0)
	v_mfma_f32_16x16x32_bf16 v[162:165], v[114:117], v[130:133], v[162:165]
	v_mfma_f32_16x16x32_bf16 v[94:97], v[106:109], v[138:141], v[94:97]
	v_mfma_f32_16x16x32_bf16 v[90:93], v[114:117], v[138:141], v[90:93]
	v_mfma_f32_16x16x32_bf16 v[78:81], v[106:109], v[146:149], v[78:81]
	s_barrier
	s_waitcnt lgkmcnt(0)
	s_setprio 1
	s_waitcnt lgkmcnt(0)
	v_mfma_f32_16x16x32_bf16 v[74:77], v[114:117], v[146:149], v[74:77]
	v_mfma_f32_16x16x32_bf16 v[154:157], v[106:109], v[122:125], v[190:193]
	v_mfma_f32_16x16x32_bf16 v[158:161], v[114:117], v[122:125], v[186:189]
	v_mfma_f32_16x16x32_bf16 v[166:169], v[106:109], v[130:133], v[174:177]
	v_mfma_f32_16x16x32_bf16 v[162:165], v[118:121], v[134:137], v[162:165]
	v_mfma_f32_16x16x32_bf16 v[94:97], v[110:113], v[142:145], v[94:97]
	v_mfma_f32_16x16x32_bf16 v[90:93], v[118:121], v[142:145], v[90:93]
	v_mfma_f32_16x16x32_bf16 v[78:81], v[110:113], v[150:153], v[78:81]
	v_mfma_f32_16x16x32_bf16 v[74:77], v[118:121], v[150:153], v[74:77]
	v_mfma_f32_16x16x32_bf16 v[154:157], v[110:113], v[126:129], v[154:157]
	v_mfma_f32_16x16x32_bf16 v[158:161], v[118:121], v[126:129], v[158:161]
	v_mfma_f32_16x16x32_bf16 v[166:169], v[110:113], v[134:137], v[166:169]
	s_setprio 0
	s_barrier
	s_add_i32 s9, 0, 0x14000
	s_add_i32 s8, s8, s43
	v_add_u32_e32 v190, s9, v217
	v_lshl_add_u64 v[210:211], s[94:95], 0, v[0:1]
	s_mov_b32 m0, s8
	ds_read_b128 v[170:173], v190
	ds_read_b128 v[174:177], v190 offset:1024
	ds_read_b128 v[186:189], v190 offset:2048
	ds_read_b128 v[190:193], v190 offset:3072
	global_load_lds_dwordx4 v[210:211], off
	v_lshl_add_u64 v[212:213], s[94:95], 0, v[200:201]
	s_add_i32 m0, s8, 0x2000
	s_nop 0
	global_load_lds_dwordx4 v[212:213], off
	s_waitcnt lgkmcnt(0)
	v_mfma_f32_16x16x32_bf16 v[182:185], v[170:173], v[122:125], v[182:185]
	v_mfma_f32_16x16x32_bf16 v[102:105], v[170:173], v[130:133], v[102:105]
	v_mfma_f32_16x16x32_bf16 v[98:101], v[186:189], v[130:133], v[98:101]
	v_mfma_f32_16x16x32_bf16 v[86:89], v[170:173], v[138:141], v[86:89]
	s_barrier
	s_waitcnt lgkmcnt(0)
	s_setprio 1
	s_waitcnt lgkmcnt(0)
	v_mfma_f32_16x16x32_bf16 v[82:85], v[186:189], v[138:141], v[82:85]
	v_mfma_f32_16x16x32_bf16 v[70:73], v[170:173], v[146:149], v[70:73]
	v_mfma_f32_16x16x32_bf16 v[66:69], v[186:189], v[146:149], v[66:69]
	v_mfma_f32_16x16x32_bf16 v[182:185], v[174:177], v[126:129], v[182:185]
	v_mfma_f32_16x16x32_bf16 v[122:125], v[186:189], v[122:125], v[178:181]
	v_mfma_f32_16x16x32_bf16 v[102:105], v[174:177], v[134:137], v[102:105]
	v_mfma_f32_16x16x32_bf16 v[98:101], v[190:193], v[134:137], v[98:101]
	v_mfma_f32_16x16x32_bf16 v[86:89], v[174:177], v[142:145], v[86:89]
	v_mfma_f32_16x16x32_bf16 v[82:85], v[190:193], v[142:145], v[82:85]
	v_mfma_f32_16x16x32_bf16 v[70:73], v[174:177], v[150:153], v[70:73]
	v_mfma_f32_16x16x32_bf16 v[66:69], v[190:193], v[150:153], v[66:69]
	v_mfma_f32_16x16x32_bf16 v[122:125], v[190:193], v[126:129], v[122:125]
	s_setprio 0
	s_mov_b32 m0, s52
	v_lshl_add_u64 v[214:215], s[4:5], 0, v[196:197]
	s_barrier
	ds_read_b128 v[126:129], v235 offset:16384
	ds_read_b128 v[130:133], v235 offset:17408
	ds_read_b128 v[134:137], v235 offset:18432
	ds_read_b128 v[138:141], v235 offset:19456
	ds_read_b128 v[142:145], v235 offset:20480
	ds_read_b128 v[146:149], v235 offset:21504
	ds_read_b128 v[150:153], v235 offset:22528
	ds_read_b128 v[178:181], v235 offset:23552
	global_load_lds_dwordx4 v[214:215], off
	v_lshl_add_u64 v[222:223], s[4:5], 0, v[198:199]
	s_mov_b32 m0, s53
	s_nop 0
	global_load_lds_dwordx4 v[222:223], off
	s_waitcnt lgkmcnt(0)
	v_mfma_f32_16x16x32_bf16 v[62:65], v[106:109], v[126:129], v[62:65]
	v_mfma_f32_16x16x32_bf16 v[58:61], v[114:117], v[126:129], v[58:61]
	v_mfma_f32_16x16x32_bf16 v[46:49], v[106:109], v[134:137], v[46:49]
	v_mfma_f32_16x16x32_bf16 v[42:45], v[114:117], v[134:137], v[42:45]
	s_barrier
	s_waitcnt lgkmcnt(0)
	s_setprio 1
	s_waitcnt lgkmcnt(0)
	v_mfma_f32_16x16x32_bf16 v[30:33], v[106:109], v[142:145], v[30:33]
	v_mfma_f32_16x16x32_bf16 v[26:29], v[114:117], v[142:145], v[26:29]
	v_mfma_f32_16x16x32_bf16 v[14:17], v[106:109], v[150:153], v[14:17]
	v_mfma_f32_16x16x32_bf16 v[10:13], v[114:117], v[150:153], v[10:13]
	v_mfma_f32_16x16x32_bf16 v[62:65], v[110:113], v[130:133], v[62:65]
	v_mfma_f32_16x16x32_bf16 v[58:61], v[118:121], v[130:133], v[58:61]
	v_mfma_f32_16x16x32_bf16 v[46:49], v[110:113], v[138:141], v[46:49]
	v_mfma_f32_16x16x32_bf16 v[42:45], v[118:121], v[138:141], v[42:45]
	v_mfma_f32_16x16x32_bf16 v[30:33], v[110:113], v[146:149], v[30:33]
	v_mfma_f32_16x16x32_bf16 v[26:29], v[118:121], v[146:149], v[26:29]
	v_mfma_f32_16x16x32_bf16 v[14:17], v[110:113], v[178:181], v[14:17]
	v_mfma_f32_16x16x32_bf16 v[10:13], v[118:121], v[178:181], v[10:13]
	s_setprio 0
	s_barrier
; #define PG8_STAGE(bufoff, gbase, voff) do { _Pragma("unroll") for (int _i = 0; _i < 2; ++_i) \
;         __builtin_amdgcn_global_load_lds((const unsigned*)((const char*)(gbase) + (voff)[_i]), (LAS unsigned*)(lds + (bufoff) + ldsw + _i * 8192), 16, 0, 0); } while (0)
; #define PG8_LDA(dst, b, h) do { _Pragma("unroll") for (int m = 0; m < 4; ++m) _Pragma("unroll") for (int k = 0; k < 2; ++k) dst[m][k] = *(const LAS bf16x8*)(lds + PG8_SA(b, h) + aoff + m * 2048 + k * 1024); } while (0)
; #define PG8_LDB(dst, b, h) do { _Pragma("unroll") for (int n = 0; n < 2; ++n) _Pragma("unroll") for (int k = 0; k < 2; ++k) dst[n][k] = *(const LAS bf16x8*)(lds + PG8_SB(b, h) + boff + n * 2048 + k * 1024); } while (0)
; #define PG8_MMA(ai, bj, At, Bt) do { __builtin_amdgcn_s_setprio(1); _Pragma("unroll") for (int m = 0; m < 4; ++m) _Pragma("unroll") for (int n = 0; n < 2; ++n) _Pragma("unroll") for (int k = 0; k < 2; ++k) \
;         acc[ai][bj][m][n] = __builtin_amdgcn_mfma_f32_16x16x32_bf16(Bt[n][k], At[m][k], acc[ai][bj][m][n], 0, 0, 0); __builtin_amdgcn_s_setprio(0); } while (0)
; #define PG8_WAIT_V(n) asm volatile("s_waitcnt vmcnt(" #n ")" ::: "memory")
; #define PG8_WAIT_L(n) asm volatile("s_waitcnt lgkmcnt(" #n ")" ::: "memory")
; #define PG8_BAR __builtin_amdgcn_s_barrier()
; #define PG8_SCHED __builtin_amdgcn_sched_barrier(0)
; template <class Epi>
; __device__ __forceinline__ void gemm_phase(LAS unsigned char* lds, const Gemm g, const Sched& S, const Epi& E) {
;     ...
;             PG8_BAR; PG8_WAIT_L(0); PG8_MMA(1, 0, At, B0); PG8_BAR; PG8_SCHED;
;             PG8_STAGE(PG8_SB(0, 1), b2 + hstepB, voffB);
;             PG8_WAIT_V(6); PG8_BAR; PG8_MMA(1, 1, At, B1); PG8_BAR;
;             PG8_LDB(B0, 1, 0); PG8_SCHED; PG8_LDA(At, 1, 0); PG8_STAGE(PG8_SA(0, 1), a2 + hstepA, voffA);
;             PG8_WAIT_L(8); PG8_BAR; PG8_WAIT_L(0); PG8_MMA(0, 0, At, B0); PG8_BAR; PG8_SCHED;
;             PG8_LDB(B1, 1, 1); PG8_STAGE(PG8_SB(1, 0), b3, voffB);
;             PG8_BAR; PG8_WAIT_L(0); PG8_MMA(0, 1, At, B1); PG8_BAR;
;             PG8_LDA(At, 1, 1); PG8_STAGE(PG8_SA(1, 0), a3, voffA);
;             PG8_BAR; PG8_WAIT_L(0); PG8_MMA(1, 0, At, B0); PG8_BAR; PG8_SCHED;
	s_add_u32 s94, s94, s76
	s_addc_u32 s95, s95, s77
	s_add_i32 s8, s9, s43
	v_lshl_add_u64 v[224:225], s[94:95], 0, v[0:1]
	s_mov_b32 m0, s8
	v_lshl_add_u64 v[226:227], s[94:95], 0, v[200:201]
	global_load_lds_dwordx4 v[224:225], off
	s_add_i32 m0, s8, 0x2000
	s_nop 0
	global_load_lds_dwordx4 v[226:227], off
	s_waitcnt vmcnt(6)
	s_waitcnt lgkmcnt(0)
	v_mfma_f32_16x16x32_bf16 v[54:57], v[170:173], v[126:129], v[54:57]
	v_mfma_f32_16x16x32_bf16 v[50:53], v[186:189], v[126:129], v[50:53]
	v_mfma_f32_16x16x32_bf16 v[38:41], v[170:173], v[134:137], v[38:41]
	v_mfma_f32_16x16x32_bf16 v[34:37], v[186:189], v[134:137], v[34:37]
	s_barrier
	s_setprio 1
	v_mfma_f32_16x16x32_bf16 v[22:25], v[170:173], v[142:145], v[22:25]
	v_mfma_f32_16x16x32_bf16 v[18:21], v[186:189], v[142:145], v[18:21]
	v_mfma_f32_16x16x32_bf16 v[6:9], v[170:173], v[150:153], v[6:9]
	v_mfma_f32_16x16x32_bf16 v[2:5], v[186:189], v[150:153], v[2:5]
	v_mfma_f32_16x16x32_bf16 v[54:57], v[174:177], v[130:133], v[54:57]
	v_mfma_f32_16x16x32_bf16 v[50:53], v[190:193], v[130:133], v[50:53]
	v_mfma_f32_16x16x32_bf16 v[38:41], v[174:177], v[138:141], v[38:41]
	v_mfma_f32_16x16x32_bf16 v[34:37], v[190:193], v[138:141], v[34:37]
	v_mfma_f32_16x16x32_bf16 v[22:25], v[174:177], v[146:149], v[22:25]
	v_mfma_f32_16x16x32_bf16 v[18:21], v[190:193], v[146:149], v[18:21]
	v_mfma_f32_16x16x32_bf16 v[6:9], v[174:177], v[178:181], v[6:9]
	v_mfma_f32_16x16x32_bf16 v[2:5], v[190:193], v[178:181], v[2:5]
	s_setprio 0
	s_add_i32 s8, 0, 0x18000
	v_add_u32_e32 v118, s8, v217
	s_barrier
	ds_read_b128 v[106:109], v118
	ds_read_b128 v[110:113], v118 offset:1024
	ds_read_b128 v[114:117], v118 offset:2048
	ds_read_b128 v[118:121], v118 offset:3072
	s_add_u32 s4, s4, s40
	s_addc_u32 s5, s5, s41
	s_mov_b32 m0, s56
	v_lshl_add_u64 v[174:175], s[4:5], 0, v[196:197]
	ds_read_b128 v[126:129], v235 offset:32768
	ds_read_b128 v[130:133], v235 offset:33792
	ds_read_b128 v[134:137], v235 offset:34816
	ds_read_b128 v[138:141], v235 offset:35840
	ds_read_b128 v[142:145], v235 offset:36864
	ds_read_b128 v[146:149], v235 offset:37888
	ds_read_b128 v[150:153], v235 offset:38912
	ds_read_b128 v[170:173], v235 offset:39936
	global_load_lds_dwordx4 v[174:175], off
	v_lshl_add_u64 v[174:175], s[4:5], 0, v[198:199]
	s_mov_b32 m0, s67
	s_nop 0
	global_load_lds_dwordx4 v[174:175], off
	s_waitcnt lgkmcnt(8)
	s_waitcnt lgkmcnt(0)
	v_mfma_f32_16x16x32_bf16 v[154:157], v[106:109], v[126:129], v[154:157]
	v_mfma_f32_16x16x32_bf16 v[190:193], v[110:113], v[130:133], v[154:157]
	v_mfma_f32_16x16x32_bf16 v[154:157], v[114:117], v[126:129], v[158:161]
	v_mfma_f32_16x16x32_bf16 v[186:189], v[118:121], v[130:133], v[154:157]
	s_barrier
	s_waitcnt lgkmcnt(0)
	s_setprio 1
	s_waitcnt lgkmcnt(0)
	v_mfma_f32_16x16x32_bf16 v[154:157], v[106:109], v[134:137], v[166:169]
	v_mfma_f32_16x16x32_bf16 v[174:177], v[110:113], v[138:141], v[154:157]
	v_mfma_f32_16x16x32_bf16 v[154:157], v[114:117], v[134:137], v[162:165]
	v_mfma_f32_16x16x32_bf16 v[94:97], v[106:109], v[142:145], v[94:97]
	v_mfma_f32_16x16x32_bf16 v[90:93], v[114:117], v[142:145], v[90:93]
	v_mfma_f32_16x16x32_bf16 v[78:81], v[106:109], v[150:153], v[78:81]
	v_mfma_f32_16x16x32_bf16 v[74:77], v[114:117], v[150:153], v[74:77]
	v_mfma_f32_16x16x32_bf16 v[162:165], v[118:121], v[138:141], v[154:157]
	v_mfma_f32_16x16x32_bf16 v[94:97], v[110:113], v[146:149], v[94:97]
	v_mfma_f32_16x16x32_bf16 v[90:93], v[118:121], v[146:149], v[90:93]
	v_mfma_f32_16x16x32_bf16 v[78:81], v[110:113], v[170:173], v[78:81]
	v_mfma_f32_16x16x32_bf16 v[74:77], v[118:121], v[170:173], v[74:77]
	s_setprio 0
	s_barrier
	s_add_i32 s4, 0, 0x1c000
	v_add_u32_e32 v178, s4, v217
	s_add_i32 s5, s8, s43
	ds_read_b128 v[154:157], v178
	ds_read_b128 v[158:161], v178 offset:1024
	ds_read_b128 v[166:169], v178 offset:2048
	ds_read_b128 v[206:209], v178 offset:3072
	v_lshl_add_u64 v[178:179], v[210:211], 0, s[60:61]
	s_mov_b32 m0, s5
	s_nop 0
	global_load_lds_dwordx4 v[178:179], off
	v_lshl_add_u64 v[178:179], v[212:213], 0, s[60:61]
	s_add_i32 m0, s5, 0x2000
	s_nop 0
	global_load_lds_dwordx4 v[178:179], off
	s_waitcnt lgkmcnt(0)
	v_mfma_f32_16x16x32_bf16 v[178:181], v[154:157], v[126:129], v[182:185]
	v_mfma_f32_16x16x32_bf16 v[122:125], v[166:169], v[126:129], v[122:125]
	v_mfma_f32_16x16x32_bf16 v[102:105], v[154:157], v[134:137], v[102:105]
	v_mfma_f32_16x16x32_bf16 v[98:101], v[166:169], v[134:137], v[98:101]
	s_barrier
	s_waitcnt lgkmcnt(0)
	s_setprio 1
	s_waitcnt lgkmcnt(0)
	v_mfma_f32_16x16x32_bf16 v[86:89], v[154:157], v[142:145], v[86:89]
	v_mfma_f32_16x16x32_bf16 v[82:85], v[166:169], v[142:145], v[82:85]
	v_mfma_f32_16x16x32_bf16 v[70:73], v[154:157], v[150:153], v[70:73]
	v_mfma_f32_16x16x32_bf16 v[66:69], v[166:169], v[150:153], v[66:69]
	v_mfma_f32_16x16x32_bf16 v[182:185], v[158:161], v[130:133], v[178:181]
	v_mfma_f32_16x16x32_bf16 v[178:181], v[206:209], v[130:133], v[122:125]
	v_mfma_f32_16x16x32_bf16 v[102:105], v[158:161], v[138:141], v[102:105]
	v_mfma_f32_16x16x32_bf16 v[98:101], v[206:209], v[138:141], v[98:101]
	v_mfma_f32_16x16x32_bf16 v[86:89], v[158:161], v[146:149], v[86:89]
	v_mfma_f32_16x16x32_bf16 v[82:85], v[206:209], v[146:149], v[82:85]
	v_mfma_f32_16x16x32_bf16 v[70:73], v[158:161], v[170:173], v[70:73]
	v_mfma_f32_16x16x32_bf16 v[66:69], v[206:209], v[170:173], v[66:69]
	s_setprio 0
	s_mov_b32 m0, s51
	v_lshl_add_u64 v[170:171], v[214:215], 0, s[60:61]
	s_barrier
; #define PG8_STAGE(bufoff, gbase, voff) do { _Pragma("unroll") for (int _i = 0; _i < 2; ++_i) \
;         __builtin_amdgcn_global_load_lds((const unsigned*)((const char*)(gbase) + (voff)[_i]), (LAS unsigned*)(lds + (bufoff) + ldsw + _i * 8192), 16, 0, 0); } while (0)
; #define PG8_LDA(dst, b, h) do { _Pragma("unroll") for (int m = 0; m < 4; ++m) _Pragma("unroll") for (int k = 0; k < 2; ++k) dst[m][k] = *(const LAS bf16x8*)(lds + PG8_SA(b, h) + aoff + m * 2048 + k * 1024); } while (0)
; #define PG8_LDB(dst, b, h) do { _Pragma("unroll") for (int n = 0; n < 2; ++n) _Pragma("unroll") for (int k = 0; k < 2; ++k) dst[n][k] = *(const LAS bf16x8*)(lds + PG8_SB(b, h) + boff + n * 2048 + k * 1024); } while (0)
; #define PG8_WAIT_V(n) asm volatile("s_waitcnt vmcnt(" #n ")" ::: "memory")
; #define PG8_WAIT_L(n) asm volatile("s_waitcnt lgkmcnt(" #n ")" ::: "memory")
; #define PG8_BAR __builtin_amdgcn_s_barrier()
; #define PG8_SCHED __builtin_amdgcn_sched_barrier(0)
; template <class Epi>
; __device__ __forceinline__ void gemm_phase(LAS unsigned char* lds, const Gemm g, const Sched& S, const Epi& E) {
;     ...
;             PG8_LDB(B1, 1, 1); PG8_STAGE(PG8_SB(1, 0), b3, voffB);
;             PG8_BAR; PG8_WAIT_L(0); PG8_MMA(0, 1, At, B1); PG8_BAR;
;             PG8_LDA(At, 1, 1); PG8_STAGE(PG8_SA(1, 0), a3, voffA);
;             PG8_BAR; PG8_WAIT_L(0); PG8_MMA(1, 0, At, B0); PG8_BAR; PG8_SCHED;
;             PG8_STAGE(PG8_SB(1, 1), b3 + hstepB, voffB);
;             PG8_WAIT_V(6); PG8_BAR; PG8_MMA(1, 1, At, B1); PG8_BAR;
;         }
;     __device__ __forceinline__ void operator()(const Acc& acc, const Unit& u, int wr, int wc, int fr, int fq, const Pre& pre) const {
;         const int row0 = u.pm * 256 + wr * 64 + fr, col0 = u.pn * 256 + wc * 32 + 8 * fq;
;         const size_t zo = (size_t)(u.zb * sOb + u.zh * sOh);
; #pragma unroll
;         for (int ai = 0; ai < 2; ++ai) {
;             f32x4 bv[4][2][2];
;             if (base) {
; #pragma unroll
;                 for (int m = 0; m < 4; ++m) { const size_t off = zo + (size_t)(row0 + ai * 128 + m * 16) * ldc + col0;
; #pragma unroll
;                     for (int bj = 0; bj < 2; ++bj)
; #pragma unroll
;                         for (int n = 0; n < 2; ++n) bv[m][bj][n] = *(const f32x4*)(base + off + bj * 128 + n * 4); }
	ds_read_b128 v[122:125], v235 offset:49152
	ds_read_b128 v[126:129], v235 offset:50176
	ds_read_b128 v[130:133], v235 offset:51200
	ds_read_b128 v[134:137], v235 offset:52224
	ds_read_b128 v[138:141], v235 offset:53248
	ds_read_b128 v[142:145], v235 offset:54272
	ds_read_b128 v[146:149], v235 offset:55296
	ds_read_b128 v[150:153], v235 offset:56320
	global_load_lds_dwordx4 v[170:171], off
	v_lshl_add_u64 v[170:171], v[222:223], 0, s[60:61]
	s_mov_b32 m0, s2
	s_nop 0
	global_load_lds_dwordx4 v[170:171], off
	s_waitcnt lgkmcnt(0)
	v_mfma_f32_16x16x32_bf16 v[62:65], v[106:109], v[122:125], v[62:65]
	v_mfma_f32_16x16x32_bf16 v[58:61], v[114:117], v[122:125], v[58:61]
	v_mfma_f32_16x16x32_bf16 v[46:49], v[106:109], v[130:133], v[46:49]
	v_mfma_f32_16x16x32_bf16 v[42:45], v[114:117], v[130:133], v[42:45]
	s_barrier
	s_waitcnt lgkmcnt(0)
	s_setprio 1
	s_waitcnt lgkmcnt(0)
	v_mfma_f32_16x16x32_bf16 v[30:33], v[106:109], v[138:141], v[30:33]
	v_mfma_f32_16x16x32_bf16 v[26:29], v[114:117], v[138:141], v[26:29]
	v_mfma_f32_16x16x32_bf16 v[14:17], v[106:109], v[146:149], v[14:17]
	v_mfma_f32_16x16x32_bf16 v[10:13], v[114:117], v[146:149], v[10:13]
	v_mfma_f32_16x16x32_bf16 v[62:65], v[110:113], v[126:129], v[62:65]
	v_mfma_f32_16x16x32_bf16 v[58:61], v[118:121], v[126:129], v[58:61]
	v_mfma_f32_16x16x32_bf16 v[46:49], v[110:113], v[134:137], v[46:49]
	v_mfma_f32_16x16x32_bf16 v[42:45], v[118:121], v[134:137], v[42:45]
	v_mfma_f32_16x16x32_bf16 v[30:33], v[110:113], v[142:145], v[30:33]
	v_mfma_f32_16x16x32_bf16 v[26:29], v[118:121], v[142:145], v[26:29]
	v_mfma_f32_16x16x32_bf16 v[14:17], v[110:113], v[150:153], v[14:17]
	v_mfma_f32_16x16x32_bf16 v[10:13], v[118:121], v[150:153], v[10:13]
	s_setprio 0
	s_barrier
	s_add_i32 s4, s4, s43
	v_lshl_add_u64 v[106:107], v[224:225], 0, s[60:61]
	s_mov_b32 m0, s4
	s_nop 0
	global_load_lds_dwordx4 v[106:107], off
	v_lshl_add_u64 v[106:107], v[226:227], 0, s[60:61]
	s_add_i32 m0, s4, 0x2000
	s_nop 0
	global_load_lds_dwordx4 v[106:107], off
	s_waitcnt vmcnt(6)
	s_waitcnt lgkmcnt(0)
	v_mfma_f32_16x16x32_bf16 v[54:57], v[154:157], v[122:125], v[54:57]
	v_mfma_f32_16x16x32_bf16 v[50:53], v[166:169], v[122:125], v[50:53]
	v_mfma_f32_16x16x32_bf16 v[38:41], v[154:157], v[130:133], v[38:41]
	v_mfma_f32_16x16x32_bf16 v[34:37], v[166:169], v[130:133], v[34:37]
	s_barrier
	s_setprio 1
	v_mfma_f32_16x16x32_bf16 v[22:25], v[154:157], v[138:141], v[22:25]
	v_mfma_f32_16x16x32_bf16 v[18:21], v[166:169], v[138:141], v[18:21]
	v_mfma_f32_16x16x32_bf16 v[6:9], v[154:157], v[146:149], v[6:9]
	v_mfma_f32_16x16x32_bf16 v[2:5], v[166:169], v[146:149], v[2:5]
	v_mfma_f32_16x16x32_bf16 v[54:57], v[158:161], v[126:129], v[54:57]
	v_mfma_f32_16x16x32_bf16 v[50:53], v[206:209], v[126:129], v[50:53]
	v_mfma_f32_16x16x32_bf16 v[38:41], v[158:161], v[134:137], v[38:41]
	v_mfma_f32_16x16x32_bf16 v[34:37], v[206:209], v[134:137], v[34:37]
	v_mfma_f32_16x16x32_bf16 v[22:25], v[158:161], v[142:145], v[22:25]
	v_mfma_f32_16x16x32_bf16 v[18:21], v[206:209], v[142:145], v[18:21]
	v_mfma_f32_16x16x32_bf16 v[6:9], v[158:161], v[150:153], v[6:9]
	v_mfma_f32_16x16x32_bf16 v[2:5], v[206:209], v[150:153], v[2:5]
	s_setprio 0
	s_add_u32 s0, s0, 0x100
	s_addc_u32 s1, s1, 0
	s_add_u32 s34, s34, 0x100
	s_addc_u32 s35, s35, 0
	s_cmp_ge_u32 s14, s73
	s_mov_b32 s4, s14
	s_barrier
	s_cbranch_scc0 .LBB0_719
	s_ashr_i32 s0, s42, 31
	s_ashr_i32 s4, s24, 31
	v_readlane_b32 s8, v253, 59
	s_mul_hi_u32 s1, s74, s42
	s_mul_i32 s0, s74, s0
	v_readlane_b32 s9, v253, 60
	s_mul_hi_u32 s5, s8, s24
	s_mul_i32 s4, s8, s4
	s_add_i32 s0, s1, s0
	s_mul_i32 s1, s75, s42
	s_add_i32 s4, s5, s4
	s_mul_i32 s5, s9, s24
	v_lshl_add_u32 v206, s97, 8, v216
	s_add_i32 s0, s0, s1
	s_mul_i32 s1, s74, s42
	s_add_i32 s4, s4, s5
	s_mul_i32 s5, s8, s24
	v_lshl_or_b32 v210, s96, 8, v234
	s_add_u32 s94, s1, s5
	v_ashrrev_i32_e32 v207, 31, v206
	s_addc_u32 s95, s0, s4
	v_ashrrev_i32_e32 v211, 31, v210
	s_mov_b64 s[0:1], -1
	s_and_b64 vcc, exec, s[78:79]
	v_mul_lo_u32 v208, s13, v206
	v_mul_lo_u32 v236, s12, v207
	v_or_b32_e32 v239, 16, v206
	v_or_b32_e32 v238, 32, v206
	v_or_b32_e32 v237, 48, v206
	s_cbranch_vccz .LBB0_722
	s_lshl_b64 s[0:1], s[94:95], 2
	v_readlane_b32 s4, v254, 7
	v_readlane_b32 s5, v254, 8
	s_add_u32 s0, s4, s0
	s_addc_u32 s1, s5, s1
	v_lshl_add_u64 v[154:155], v[210:211], 2, s[0:1]
	v_mad_u64_u32 v[212:213], s[0:1], s12, v206, 0
	v_mul_lo_u32 v124, s13, v239
	v_mad_u64_u32 v[122:123], s[0:1], s12, v239, 0
	v_mul_lo_u32 v140, s13, v238
	v_mad_u64_u32 v[138:139], s[0:1], s12, v238, 0
	v_mul_lo_u32 v158, s13, v237
	v_mad_u64_u32 v[156:157], s[0:1], s12, v237, 0
	v_add3_u32 v213, v213, v236, v208
	v_add3_u32 v123, v123, v236, v124
	v_add3_u32 v139, v139, v236, v140
	v_add3_u32 v157, v157, v236, v158
	v_lshl_add_u64 v[118:119], v[212:213], 2, v[154:155]
	v_lshl_add_u64 v[134:135], v[122:123], 2, v[154:155]
	v_lshl_add_u64 v[150:151], v[138:139], 2, v[154:155]
	v_lshl_add_u64 v[170:171], v[156:157], 2, v[154:155]
	flat_load_dwordx4 v[106:109], v[118:119]
	flat_load_dwordx4 v[110:113], v[118:119] offset:16
	flat_load_dwordx4 v[114:117], v[118:119] offset:512
	s_nop 0
	flat_load_dwordx4 v[118:121], v[118:119] offset:528
	s_nop 0
	flat_load_dwordx4 v[122:125], v[134:135]
	flat_load_dwordx4 v[126:129], v[134:135] offset:16
	flat_load_dwordx4 v[130:133], v[134:135] offset:512
	s_nop 0
	flat_load_dwordx4 v[134:137], v[134:135] offset:528
	s_nop 0
	flat_load_dwordx4 v[138:141], v[150:151]
	flat_load_dwordx4 v[142:145], v[150:151] offset:16
	flat_load_dwordx4 v[146:149], v[150:151] offset:512
	s_nop 0
	flat_load_dwordx4 v[150:153], v[150:151] offset:528
	s_nop 0
	flat_load_dwordx4 v[154:157], v[170:171]
	flat_load_dwordx4 v[158:161], v[170:171] offset:16
	flat_load_dwordx4 v[166:169], v[170:171] offset:512
	s_nop 0
	flat_load_dwordx4 v[170:173], v[170:171] offset:528
	s_mov_b64 s[0:1], 0
